# phase 4: every other group of eight workgroups starts its seven tiles one s_sleep 127 late (on top of the previous version)
# baseline (speedup 1.0000x reference)
.Lgprio_5:
	s_cmpk_lg_u32 s70, 0x100
	s_cbranch_scc1 .Lp4_go
	s_bitcmp1_b32 s2, 3
	s_cbranch_scc0 .Lp4_go
	s_sleep 127
